# DF attention loop: fold per-item base offsets into tile pointers at item setup, loop-top address math removed
# speedup vs baseline: 1.0146x; 1.0034x over previous
; DI int TID() { int t = threadIdx.x; asm volatile("" : "+v"(t)); return t; }
; DI void attn_item_df2(const bf16_t* Qb, const bf16_t* Kb, size_t mstride, const bf16_t* VTb, int q0, int nkt  , float cs,
;                       bf16_t* Orow, float lam, float outscale, const float* subw, char* smem) {
;   constexpr int DQK = 64, KSTR = 144, KT_BYTES = 2 * 64 * KSTR, VSTR = 144, VT_BYTES = 128 * VSTR;
;   const int tid = TID(), lane = tid & 63, wv = tid >> 6, l31 = lane & 31, hh = lane >> 5;
;   const int m = wv >> 2, wq = wv & 3;
;   const int qp = q0 + wq * 32 + l31;
;   bf16x8 qf[4];
;   {
;     const bf16_t* qptr = Qb + m * mstride + (size_t)qp * DQK + hh * 8;
; #pragma unroll
;     for (int s = 0; s < 4; ++s) qf[s] = *(const bf16x8*)(qptr + s * 16);
;   }
;   f32x16 oacc[4];
; #pragma unroll
;   for (int db = 0; db < 4; ++db)
; #pragma unroll
;     for (int i = 0; i < 16; ++i) oacc[db][i] = 0.f;
;   float mrun = -1e30f, lrun = 0.f;
;   uint4 kreg0, kreg1, vreg0, vreg1;
;   const int c1 = tid + NTHR;
;   const int kgo0 = (tid >> 9) * (int)mstride + ((tid & 511) >> 3) * DQK + (tid & 7) * 8, kgo1 = (c1 >> 9) * (int)mstride + ((c1 & 511) >> 3) * DQK + (c1 & 7) * 8;
;   const int klo0 = ((tid >> 9) * 64 + ((tid & 511) >> 3)) * KSTR + (tid & 7) * 16, klo1 = ((c1 >> 9) * 64 + ((c1 & 511) >> 3)) * KSTR + (c1 & 7) * 16;
;   const int vgo0 = (tid >> 3) * PL + (tid & 7) * 8, vgo1 = (c1 >> 3) * PL + (tid & 7) * 8;
;   const int vlo0 = (tid >> 3) * VSTR + (tid & 7) * 16, vlo1 = (c1 >> 3) * VSTR + (tid & 7) * 16;
;   const int kfo = (m * 64 + l31) * KSTR + hh * 16;
;   const int vfo = 2 * KT_BYTES + l31 * VSTR + hh * 16;
; DI void phase_attn_df(const Params& p, bool do_ctx, char* smem) {
;     ...
;   for (int q = slot; q < 4 * 64; q += nslots) {
;     int bh = (q >> 6) * 8 + xcd, qb = (q & 63) + 2;
;     int b = bh >> 3, h = bh & 7;
;     attn_item_df2(Q + (size_t)bh * 2 * PL * 64, K + (size_t)bh * 2 * PL * 64, (size_t)PL * 64, VT + (size_t)bh * 128 * PL, qb * 128, PL / 64, cs,
.LBB0_256:
	s_ashr_i32 s0, s36, 3
	s_and_b32 s0, s0, -8
	s_or_b32 s0, s0, s37
	s_mul_hi_i32 s1, s0, 0x210000
	s_mul_i32 s0, s0, 0x210000
	s_add_u32 s30, s52, s0
	s_addc_u32 s31, s53, s1
	v_readlane_b32 s3, v252, 30
	s_add_u32 s28, s3, s0
	v_readlane_b32 s3, v252, 31
	v_mov_b32_e32 v165, v167
	s_addc_u32 s29, s3, s1
	v_readlane_b32 s3, v252, 32
	s_add_u32 s38, s3, s0
	v_add_u32_e32 v0, 0x200, v165
	v_ashrrev_i32_e32 v30, 9, v165
	v_bfe_u32 v31, v165, 3, 6
	v_and_b32_e32 v32, 7, v165
	v_readlane_b32 s3, v252, 33
	v_mul_i32_i24_e32 v1, 0x84000, v30
	v_lshlrev_b32_e32 v2, 6, v31
	v_lshlrev_b32_e32 v3, 3, v32
	v_ashrrev_i32_e32 v34, 9, v0
	s_addc_u32 s39, s3, s1
	v_or3_b32 v170, v2, v1, v3
	v_mul_i32_i24_e32 v1, 0x84000, v34
	v_ashrrev_i32_e32 v35, 3, v165
	s_movk_i32 s3, 0x2100
	v_ashrrev_i32_e32 v36, 3, v0
	v_or3_b32 v172, v1, v2, v3
	v_mul_lo_u32 v1, v35, s3
	v_mul_lo_u32 v0, v36, s3
	v_ashrrev_i32_e32 v171, 31, v170
	v_or_b32_e32 v174, v1, v3
	v_or_b32_e32 v176, v0, v3
	v_lshlrev_b64 v[0:1], 1, v[170:171]
	v_ashrrev_i32_e32 v173, 31, v172
	v_lshl_add_u64 v[4:5], s[28:29], 0, v[0:1]
	v_lshlrev_b64 v[2:3], 1, v[172:173]
	v_ashrrev_i32_e32 v175, 31, v174
	v_lshl_add_u64 v[6:7], s[28:29], 0, v[2:3]
	global_load_dwordx4 v[8:11], v[4:5], off
	global_load_dwordx4 v[12:15], v[6:7], off
	v_lshlrev_b64 v[4:5], 1, v[174:175]
	v_ashrrev_i32_e32 v177, 31, v176
	v_lshl_add_u64 v[24:25], s[38:39], 0, v[4:5]
	v_lshlrev_b64 v[6:7], 1, v[176:177]
	v_lshl_add_u64 v[26:27], s[38:39], 0, v[6:7]
	global_load_dwordx4 v[16:19], v[24:25], off
	global_load_dwordx4 v[20:23], v[26:27], off
	s_lshl_b32 s3, s36, 7
	v_bfe_u32 v169, v165, 6, 2
	v_lshl_or_b32 v33, v30, 6, v31
	v_lshlrev_b32_e32 v30, 4, v32
	s_movk_i32 s27, 0x90
	s_and_b32 s3, s3, 0x1f80
	v_and_b32_e32 v40, 31, v165
	v_ashrrev_i32_e32 v214, 8, v165
	v_lshlrev_b32_e32 v37, 5, v169
	v_mad_u64_u32 v[32:33], s[24:25], v33, s27, v[30:31]
	v_lshl_or_b32 v31, v34, 6, v31
	s_addk_i32 s3, 0x100
	v_mul_hi_i32_i24_e32 v29, 0x108000, v214
	v_mul_i32_i24_e32 v28, 0x108000, v214
	v_mad_u64_u32 v[178:179], s[24:25], v35, s27, v[30:31]
	v_mad_u64_u32 v[180:181], s[24:25], v36, s27, v[30:31]
	v_mad_u64_u32 v[30:31], s[24:25], v31, s27, v[30:31]
	v_or3_b32 v164, v37, s3, v40
	v_bfe_u32 v41, v165, 5, 1
	v_lshl_add_u64 v[28:29], s[30:31], 0, v[28:29]
	s_add_u32 s24, s28, 0x2000
	v_lshlrev_b32_e32 v140, 7, v164
	s_addc_u32 s25, s29, 0
	v_lshl_add_u64 v[28:29], v[28:29], 0, v[140:141]
	v_lshlrev_b32_e32 v140, 4, v41
	v_add_u32_e32 v217, 0, v32
	v_add_u32_e32 v216, 0, v30
	v_lshl_add_u64 v[30:31], s[24:25], 0, v[0:1]
	v_lshl_add_u64 v[32:33], s[24:25], 0, v[2:3]
	v_lshl_add_u64 v[28:29], v[28:29], 0, v[140:141]
	v_add_u32_e32 v215, 0, v178
	v_add_u32_e32 v181, 0, v180
	global_load_dwordx4 v[142:145], v[28:29], off
	global_load_dwordx4 v[136:139], v[28:29], off offset:32
	global_load_dwordx4 v[132:135], v[28:29], off offset:64
	global_load_dwordx4 v[128:131], v[28:29], off offset:96
	v_and_b32_e32 v179, 63, v165
	v_lshlrev_b32_e32 v168, 3, v41
	v_mul_u32_u24_e32 v56, 0x90, v40
	s_waitcnt vmcnt(7)
	ds_write_b128 v217, v[8:11]
	s_waitcnt vmcnt(6)
	ds_write_b128 v216, v[12:15]
	s_waitcnt vmcnt(5)
	ds_write_b128 v215, v[16:19] offset:36864
	s_waitcnt vmcnt(4)
	ds_write_b128 v181, v[20:23] offset:36864
	s_waitcnt lgkmcnt(0)
	s_barrier
; #define PIN() do { asm volatile("" ::: "memory"); __builtin_amdgcn_sched_barrier(0); } while (0)
; #define D2_GLOAD(t_) do { const bf16_t* kp_ = Kb + (size_t)(t_) * 64 * DQK; const bf16_t* vp_ = VTb + (t_) * 64; \
;     kreg0 = *(const uint4*)(kp_ + kgo0); kreg1 = *(const uint4*)(kp_ + kgo1); vreg0 = *(const uint4*)(vp_ + vgo0); vreg1 = *(const uint4*)(vp_ + vgo1); } while (0)
; #define D2_SSTORE(ks_, vs_) do { char* kb_ = smem + (ks_) * KT_BYTES; char* vb_ = smem + 2 * KT_BYTES + (vs_) * VT_BYTES; \
;     *(uint4*)(kb_ + klo0) = kreg0; *(uint4*)(kb_ + klo1) = kreg1; *(uint4*)(vb_ + vlo0) = vreg0; *(uint4*)(vb_ + vlo1) = vreg1; } while (0)
; #define D2_RESCALE(mx_) do { if (__any(((mx_) - mrun) * cs > 8.f)) { const float mnew = fmaxf(mrun, (mx_)); const float alpha = __builtin_amdgcn_exp2f((mrun - mnew) * cs); \
;       mrun = mnew; lrun *= alpha; \
;       _Pragma("unroll") for (int db = 0; db < 4; ++db) _Pragma("unroll") for (int i = 0; i < 16; ++i) oacc[db][i] *= alpha; } } while (0)
; #define D2_HALFMAX(mx_) do { const auto rr_ = __builtin_amdgcn_permlane32_swap(__float_as_uint(mx_), __float_as_uint(mx_), false, false); \
;       mx_ = fmaxf(__uint_as_float(rr_[0]), __uint_as_float(rr_[1])); } while (0)
; DI void attn_item_df2(const bf16_t* Qb, const bf16_t* Kb, size_t mstride, const bf16_t* VTb, int q0, int nkt  , float cs,
;                       bf16_t* Orow, float lam, float outscale, const float* subw, char* smem) {
;     ...
;   D2_GLOAD(0); D2_SSTORE(0, 0); __syncthreads();
;   D2_GLOAD(1); PIN();
;   { const f32x2_t cs2 = {cs, cs}, mc2 = {0.f, 0.f}; f32x2_t ps2 = {0.f, 0.f}; D2_SEG_A(pA, pB, 0, false); (void)cs2; (void)mc2; (void)ps2; }
;   { float mx0 = pA[0][0];
; #pragma unroll
;     for (int i = 1; i < 16; ++i) mx0 = fmaxf(mx0, pA[0][i]);
; #pragma unroll
;     for (int i = 0; i < 16; ++i) mx0 = fmaxf(mx0, pA[1][i]);
;     D2_HALFMAX(mx0); D2_RESCALE(mx0); }
;   PIN();
;   D2_SSTORE(1, 1);
;   __syncthreads();
;   for (int j = 1; j < nkt - 1; j += 2) {
	global_load_dwordx4 v[8:11], v[30:31], off
	global_load_dwordx4 v[12:15], v[32:33], off
	s_nop 0
	global_load_dwordx4 v[32:35], v[24:25], off offset:128
	global_load_dwordx4 v[36:39], v[26:27], off offset:128
	v_lshl_or_b32 v16, v214, 6, v40
	v_mad_u64_u32 v[16:17], s[24:25], v16, s27, v[140:141]
	v_add_u32_e32 v219, 0, v16
	ds_read_b128 v[16:19], v219
	ds_read_b128 v[20:23], v219 offset:32
	ds_read_b128 v[24:27], v219 offset:4608
	ds_read_b128 v[28:31], v219 offset:4640
	ds_read_b128 v[40:43], v219 offset:64
	ds_read_b128 v[44:47], v219 offset:96
	ds_read_b128 v[48:51], v219 offset:4672
	ds_read_b128 v[52:55], v219 offset:4704
	s_waitcnt vmcnt(7) lgkmcnt(7)
	v_mfma_f32_32x32x16_bf16 v[80:95], v[16:19], v[142:145], 0
	s_waitcnt lgkmcnt(5)
	v_mfma_f32_32x32x16_bf16 v[64:79], v[24:27], v[142:145], 0
	s_waitcnt vmcnt(6)
	v_mfma_f32_32x32x16_bf16 v[80:95], v[20:23], v[136:139], v[80:95]
	s_waitcnt lgkmcnt(4)
	v_mfma_f32_32x32x16_bf16 v[64:79], v[28:31], v[136:139], v[64:79]
	s_waitcnt vmcnt(5) lgkmcnt(3)
	v_mfma_f32_32x32x16_bf16 v[80:95], v[40:43], v[132:135], v[80:95]
	s_waitcnt lgkmcnt(1)
	v_mfma_f32_32x32x16_bf16 v[64:79], v[48:51], v[132:135], v[64:79]
	s_waitcnt vmcnt(4)
	v_mfma_f32_32x32x16_bf16 v[80:95], v[44:47], v[128:131], v[80:95]
	s_waitcnt lgkmcnt(0)
	v_mfma_f32_32x32x16_bf16 v[64:79], v[52:55], v[128:131], v[64:79]
	s_nop 9
	v_max_f32_e32 v16, v81, v81
	v_max_f32_e32 v17, v80, v80
	v_max_f32_e32 v16, v17, v16
	v_max3_f32 v16, v16, v82, v83
	v_max3_f32 v16, v16, v84, v85
	v_max3_f32 v16, v16, v86, v87
	v_max3_f32 v16, v16, v88, v89
	v_max3_f32 v16, v16, v90, v91
	v_max3_f32 v16, v16, v92, v93
	v_max3_f32 v16, v16, v94, v95
	v_max3_f32 v16, v16, v64, v65
	v_max3_f32 v16, v16, v66, v67
	v_max3_f32 v16, v16, v68, v69
	v_max3_f32 v16, v16, v70, v71
	v_max3_f32 v16, v16, v72, v73
	v_max3_f32 v16, v16, v74, v75
	v_max3_f32 v16, v16, v76, v77
	v_max3_f32 v16, v16, v78, v79
	v_mov_b32_e32 v17, v16
	s_nop 1
	v_permlane32_swap_b32_e32 v16, v17
	v_max_f32_e32 v17, v17, v17
	v_max_f32_e32 v16, v16, v16
	v_max_f32_e32 v16, v16, v17
	v_max_f32_e32 v40, 0xf149f2ca, v16
	v_add_f32_e32 v17, 0x7149f2ca, v16
	v_sub_f32_e32 v16, 0xf149f2ca, v40
	v_mul_f32_e32 v16, 0x3e38aa3b, v16
	v_exp_f32_e32 v16, v16
	v_mul_f32_e32 v17, 0x3e38aa3b, v17
	v_cmp_lt_f32_e32 vcc, s5, v17
	s_cmp_eq_u64 vcc, 0
	v_mul_f32_e32 v16, 0, v16
	s_cselect_b64 vcc, -1, 0
	v_cndmask_b32_e64 v16, v16, 0, vcc
	v_mov_b32_e32 v17, v16
	v_mov_b32_e32 v18, v16
	v_mov_b32_e32 v19, v16
	v_mov_b32_e32 v20, v16
	v_mov_b32_e32 v21, v16
	v_mov_b32_e32 v22, v16
	v_mov_b32_e32 v23, v16
	v_mov_b32_e32 v24, v16
	v_mov_b32_e32 v25, v16
	v_mov_b32_e32 v26, v16
	v_mov_b32_e32 v27, v16
	v_mov_b32_e32 v28, v16
	v_mov_b32_e32 v29, v16
	v_mov_b32_e32 v30, v16
	v_mov_b32_e32 v31, v16
	v_cndmask_b32_e32 v220, v40, v208, vcc
	s_waitcnt vmcnt(3)
	ds_write_b128 v217, v[8:11] offset:18432
	s_waitcnt vmcnt(2)
	ds_write_b128 v216, v[12:15] offset:18432
	s_waitcnt vmcnt(1)
	ds_write_b128 v215, v[32:35] offset:55296
	s_waitcnt vmcnt(0)
	ds_write_b128 v181, v[36:39] offset:55296
	v_add3_u32 v218, 0, v56, v140
	v_lshl_add_u64 v[182:183], s[20:21], 0, v[4:5]
	v_lshl_add_u64 v[184:185], s[20:21], 0, v[6:7]
	v_lshl_add_u64 v[186:187], s[20:21], 0, v[0:1]
	v_lshl_add_u64 v[188:189], s[20:21], 0, v[2:3]
	v_lshl_add_u64 v[182:183], v[182:183], 0, s[0:1]
	v_lshl_add_u64 v[184:185], v[184:185], 0, s[0:1]
	v_lshl_add_u64 v[186:187], v[186:187], 0, s[0:1]
	v_lshl_add_u64 v[188:189], v[188:189], 0, s[0:1]
	s_mov_b64 s[98:99], 0xeb00000
	v_lshl_add_u64 v[182:183], v[182:183], 0, s[98:99]
	v_lshl_add_u64 v[184:185], v[184:185], 0, s[98:99]
	s_mov_b64 s[98:99], 0xa904000
	v_lshl_add_u64 v[186:187], v[186:187], 0, s[98:99]
	v_lshl_add_u64 v[188:189], v[188:189], 0, s[98:99]
	v_mov_b64_e32 v[62:63], v[30:31]
	v_mov_b64_e32 v[46:47], v[30:31]
	v_mov_b64_e32 v[0:1], v[16:17]
	s_mov_b32 s30, 0
	s_mov_b32 s3, -1
	v_mov_b64_e32 v[60:61], v[28:29]
	v_mov_b64_e32 v[58:59], v[26:27]
	v_mov_b64_e32 v[56:57], v[24:25]
	v_mov_b64_e32 v[54:55], v[22:23]
	v_mov_b64_e32 v[52:53], v[20:21]
	v_mov_b64_e32 v[50:51], v[18:19]
	v_mov_b64_e32 v[48:49], v[16:17]
	v_mov_b64_e32 v[44:45], v[28:29]
	v_mov_b64_e32 v[42:43], v[26:27]
	v_mov_b64_e32 v[40:41], v[24:25]
	v_mov_b64_e32 v[38:39], v[22:23]
	v_mov_b64_e32 v[36:37], v[20:21]
	v_mov_b64_e32 v[34:35], v[18:19]
	v_mov_b64_e32 v[32:33], v[16:17]
	v_mov_b64_e32 v[2:3], v[18:19]
	v_mov_b64_e32 v[4:5], v[20:21]
	v_mov_b64_e32 v[6:7], v[22:23]
	v_mov_b64_e32 v[8:9], v[24:25]
	v_mov_b64_e32 v[10:11], v[26:27]
	v_mov_b64_e32 v[12:13], v[28:29]
	v_mov_b64_e32 v[14:15], v[30:31]
	v_mov_b32_e32 v191, v16
	s_waitcnt lgkmcnt(0)
	s_barrier
	s_branch .LBB0_258

.LBB0_258:
	global_load_dwordx4 v[158:161], v[186:187], off
	global_load_dwordx4 v[154:157], v[188:189], off
	global_load_dwordx4 v[150:153], v[182:183], off offset:256
	global_load_dwordx4 v[146:149], v[184:185], off offset:256
	ds_read_b128 v[96:99], v219 offset:18432
	ds_read_b128 v[222:225], v219 offset:18464
	ds_read_b128 v[100:103], v219 offset:23040
	ds_read_b128 v[226:229], v219 offset:23072
	ds_read_b128 v[230:233], v219 offset:18496
	ds_read_b128 v[234:237], v219 offset:18528
	ds_read_b128 v[238:241], v219 offset:23104
	ds_read_b128 v[242:245], v219 offset:23136
	v_mul_f32_e32 v190, 0x3e38aa3b, v220
	s_waitcnt lgkmcnt(7)
	v_mfma_f32_32x32x16_bf16 v[112:127], v[96:99], v[142:145], 0
	v_fma_f32 v80, v80, s78, -v190
	v_fma_f32 v81, v81, s78, -v190
	v_fma_f32 v82, v82, s78, -v190
	v_fma_f32 v83, v83, s78, -v190
	v_exp_f32_e32 v80, v80
	v_exp_f32_e32 v81, v81
	v_exp_f32_e32 v82, v82
	v_exp_f32_e32 v83, v83
	v_pk_add_f32 v[96:97], v[80:81], 0 op_sel_hi:[1,0]
	v_cvt_pk_bf16_f32 v80, v80, v81
	v_pk_add_f32 v[246:247], v[82:83], v[96:97]
	v_cvt_pk_bf16_f32 v81, v82, v83
	s_waitcnt lgkmcnt(5)
	v_mfma_f32_32x32x16_bf16 v[96:111], v[100:103], v[142:145], 0
	v_mfma_f32_32x32x16_bf16 v[112:127], v[222:225], v[136:139], v[112:127]
	v_fma_f32 v82, v84, s78, -v190
	v_fma_f32 v83, v85, s78, -v190
	v_fma_f32 v84, v86, s78, -v190
	v_fma_f32 v85, v87, s78, -v190
	v_exp_f32_e32 v82, v82
	v_exp_f32_e32 v83, v83
	v_exp_f32_e32 v84, v84
	v_exp_f32_e32 v85, v85
	v_pk_add_f32 v[86:87], v[82:83], v[246:247]
	v_cvt_pk_bf16_f32 v82, v82, v83
	v_pk_add_f32 v[86:87], v[84:85], v[86:87]
	v_cvt_pk_bf16_f32 v83, v84, v85
	s_waitcnt lgkmcnt(4)
	v_mfma_f32_32x32x16_bf16 v[96:111], v[226:229], v[136:139], v[96:111]
	s_waitcnt lgkmcnt(3)
	v_mfma_f32_32x32x16_bf16 v[112:127], v[230:233], v[132:135], v[112:127]
	v_fma_f32 v84, v88, s78, -v190
	v_fma_f32 v85, v89, s78, -v190
	v_fma_f32 v88, v90, s78, -v190
	v_fma_f32 v89, v91, s78, -v190
	v_exp_f32_e32 v84, v84
	v_exp_f32_e32 v85, v85
	v_exp_f32_e32 v88, v88
	v_exp_f32_e32 v89, v89
	v_pk_add_f32 v[86:87], v[84:85], v[86:87]
	v_cvt_pk_bf16_f32 v84, v84, v85
	v_pk_add_f32 v[86:87], v[88:89], v[86:87]
	v_cvt_pk_bf16_f32 v85, v88, v89
	s_waitcnt lgkmcnt(1)
	v_mfma_f32_32x32x16_bf16 v[96:111], v[238:241], v[132:135], v[96:111]
	v_mfma_f32_32x32x16_bf16 v[112:127], v[234:237], v[128:131], v[112:127]
	v_fma_f32 v88, v92, s78, -v190
	v_fma_f32 v89, v93, s78, -v190
	v_fma_f32 v90, v94, s78, -v190
	v_fma_f32 v91, v95, s78, -v190
	v_exp_f32_e32 v88, v88
	v_exp_f32_e32 v89, v89
	v_exp_f32_e32 v90, v90
	v_exp_f32_e32 v91, v91
	v_pk_add_f32 v[86:87], v[88:89], v[86:87]
	s_nop 0
	v_pk_add_f32 v[246:247], v[90:91], v[86:87]
	v_cvt_pk_bf16_f32 v86, v88, v89
	v_cvt_pk_bf16_f32 v87, v90, v91
	s_waitcnt lgkmcnt(0)
	v_mfma_f32_32x32x16_bf16 v[96:111], v[242:245], v[128:131], v[96:111]
	s_mul_i32 s27, s30, 0x4800
	s_add_i32 s24, s30, 1
	v_add_u32_e32 v221, s27, v218
	s_cmp_lg_u32 s30, 2
	ds_read_b128 v[88:91], v221 offset:36864
	ds_read_b128 v[92:95], v221 offset:41472
	ds_read_b128 v[222:225], v221 offset:46080
	ds_read_b128 v[226:229], v221 offset:50688
	s_cselect_b32 s24, s24, 0
	s_add_i32 s25, s24, 1
	s_cmp_lg_u32 s24, 2
	s_cselect_b32 s30, s25, 0
	s_mul_i32 s25, s30, 0x4800
	s_add_i32 s27, s25, 0
	v_add_u32_e32 v248, s27, v180
	v_add_u32_e32 v249, s27, v178
	ds_read_b128 v[230:233], v221 offset:36896
	ds_read_b128 v[234:237], v221 offset:41504
	ds_read_b128 v[238:241], v221 offset:46112
	ds_read_b128 v[242:245], v221 offset:50720
	s_waitcnt lgkmcnt(7)
	v_mfma_f32_32x32x16_bf16 v[16:31], v[88:91], v[80:83], v[16:31]
	v_fma_f32 v64, v64, s78, -v190
	v_fma_f32 v65, v65, s78, -v190
	v_fma_f32 v66, v66, s78, -v190
	v_fma_f32 v67, v67, s78, -v190
	v_exp_f32_e32 v64, v64
	v_exp_f32_e32 v65, v65
	v_exp_f32_e32 v66, v66
	v_exp_f32_e32 v67, v67
	v_pk_add_f32 v[88:89], v[64:65], v[246:247]
	v_cvt_pk_bf16_f32 v64, v64, v65
	v_pk_add_f32 v[88:89], v[66:67], v[88:89]
	v_cvt_pk_bf16_f32 v65, v66, v67
	s_waitcnt lgkmcnt(6)
	v_mfma_f32_32x32x16_bf16 v[48:63], v[92:95], v[80:83], v[48:63]
	s_waitcnt lgkmcnt(5)
	v_mfma_f32_32x32x16_bf16 v[32:47], v[222:225], v[80:83], v[32:47]
	v_fma_f32 v66, v68, s78, -v190
	v_fma_f32 v67, v69, s78, -v190
	v_fma_f32 v68, v70, s78, -v190
	v_fma_f32 v69, v71, s78, -v190
	v_exp_f32_e32 v66, v66
	v_exp_f32_e32 v67, v67
	v_exp_f32_e32 v68, v68
	v_exp_f32_e32 v69, v69
	v_pk_add_f32 v[70:71], v[66:67], v[88:89]
	v_cvt_pk_bf16_f32 v66, v66, v67
	v_pk_add_f32 v[222:223], v[68:69], v[70:71]
	v_cvt_pk_bf16_f32 v67, v68, v69
	s_waitcnt lgkmcnt(4)
	v_mfma_f32_32x32x16_bf16 v[0:15], v[226:229], v[80:83], v[0:15]
	s_waitcnt vmcnt(3)
	ds_write_b128 v217, v[158:161]
	ds_read_b128 v[68:71], v221 offset:36928
	ds_read_b128 v[80:83], v221 offset:41536
	ds_read_b128 v[88:91], v221 offset:46144
	ds_read_b128 v[92:95], v221 offset:50752
	s_waitcnt lgkmcnt(8)
	v_mfma_f32_32x32x16_bf16 v[16:31], v[230:233], v[84:87], v[16:31]
	v_fma_f32 v72, v72, s78, -v190
	v_fma_f32 v73, v73, s78, -v190
	v_fma_f32 v74, v74, s78, -v190
	v_fma_f32 v75, v75, s78, -v190
	v_exp_f32_e32 v72, v72
	v_exp_f32_e32 v73, v73
	v_exp_f32_e32 v74, v74
	v_exp_f32_e32 v75, v75
	v_pk_add_f32 v[158:159], v[72:73], v[222:223]
	v_cvt_pk_bf16_f32 v72, v72, v73
	v_pk_add_f32 v[158:159], v[74:75], v[158:159]
	v_cvt_pk_bf16_f32 v73, v74, v75
	s_waitcnt lgkmcnt(7)
	v_mfma_f32_32x32x16_bf16 v[48:63], v[234:237], v[84:87], v[48:63]
	s_waitcnt lgkmcnt(6)
	v_mfma_f32_32x32x16_bf16 v[32:47], v[238:241], v[84:87], v[32:47]
	v_fma_f32 v74, v76, s78, -v190
	v_fma_f32 v75, v77, s78, -v190
	v_fma_f32 v76, v78, s78, -v190
	v_fma_f32 v77, v79, s78, -v190
	v_exp_f32_e32 v74, v74
	v_exp_f32_e32 v75, v75
	v_exp_f32_e32 v76, v76
	v_exp_f32_e32 v77, v77
	v_pk_add_f32 v[78:79], v[74:75], v[158:159]
	v_cvt_pk_bf16_f32 v74, v74, v75
	v_pk_add_f32 v[222:223], v[76:77], v[78:79]
	v_cvt_pk_bf16_f32 v75, v76, v77
	s_waitcnt lgkmcnt(5)
	v_mfma_f32_32x32x16_bf16 v[0:15], v[242:245], v[84:87], v[0:15]
	s_waitcnt vmcnt(2)
	ds_write_b128 v216, v[154:157]
	ds_read_b128 v[76:79], v221 offset:36960
	ds_read_b128 v[84:87], v221 offset:41568
	ds_read_b128 v[154:157], v221 offset:46176
	ds_read_b128 v[158:161], v221 offset:50784
	s_waitcnt lgkmcnt(8)
	v_mfma_f32_32x32x16_bf16 v[16:31], v[68:71], v[64:67], v[16:31]
	s_mov_b32 s27, 0xf149f2ca
	v_max3_f32 v68, v112, s27, v113
	v_max3_f32 v68, v68, v114, v115
	v_max3_f32 v68, v68, v116, v117
	v_max3_f32 v68, v68, v118, v119
	s_waitcnt lgkmcnt(7)
	v_mfma_f32_32x32x16_bf16 v[48:63], v[80:83], v[64:67], v[48:63]
	s_waitcnt lgkmcnt(6)
	v_mfma_f32_32x32x16_bf16 v[32:47], v[88:91], v[64:67], v[32:47]
	v_max3_f32 v68, v68, v120, v121
	v_max3_f32 v68, v68, v122, v123
	v_max3_f32 v68, v68, v124, v125
	v_max3_f32 v68, v68, v126, v127
	s_waitcnt lgkmcnt(5)
	v_mfma_f32_32x32x16_bf16 v[0:15], v[92:95], v[64:67], v[0:15]
	s_waitcnt vmcnt(1)
	ds_write_b128 v249, v[150:153] offset:36864
	s_waitcnt lgkmcnt(4)
	v_mfma_f32_32x32x16_bf16 v[16:31], v[76:79], v[72:75], v[16:31]
	v_max3_f32 v64, v68, v96, v97
	v_max3_f32 v64, v64, v98, v99
	v_max3_f32 v64, v64, v100, v101
	v_max3_f32 v64, v64, v102, v103
	s_waitcnt lgkmcnt(3)
	v_mfma_f32_32x32x16_bf16 v[48:63], v[84:87], v[72:75], v[48:63]
	s_waitcnt lgkmcnt(2)
	v_mfma_f32_32x32x16_bf16 v[32:47], v[154:157], v[72:75], v[32:47]
	v_max3_f32 v64, v64, v104, v105
	v_max3_f32 v64, v64, v106, v107
	v_max3_f32 v64, v64, v108, v109
	v_max3_f32 v64, v64, v110, v111
	s_waitcnt lgkmcnt(1)
	v_mfma_f32_32x32x16_bf16 v[0:15], v[158:161], v[72:75], v[0:15]
	s_waitcnt vmcnt(0)
	ds_write_b128 v248, v[146:149] offset:36864
	v_add_f32_e32 v65, v222, v223
	v_add_f32_e32 v158, v191, v65
	v_mov_b32_e32 v65, v64
	s_nop 1
	v_permlane32_swap_b32_e32 v64, v65
	v_max_f32_e32 v64, v64, v65
	v_sub_f32_e32 v65, v64, v220
	v_mul_f32_e32 v65, 0x3e38aa3b, v65
	v_cmp_lt_f32_e32 vcc, s5, v65
	s_cbranch_vccz .LBB0_260
	v_max_f32_e32 v64, v64, v64
	v_max_f32_e32 v65, v220, v220
	v_max_f32_e32 v65, v65, v64
	v_sub_f32_e32 v64, v220, v65
	v_mul_f32_e32 v64, 0x3e38aa3b, v64
	v_exp_f32_e32 v64, v64
	v_mul_f32_e32 v190, 0x3e38aa3b, v65
	v_mov_b32_e32 v220, v65
	v_pk_mul_f32 v[30:31], v[30:31], v[64:65] op_sel_hi:[1,0]
	v_pk_mul_f32 v[28:29], v[28:29], v[64:65] op_sel_hi:[1,0]
	v_pk_mul_f32 v[26:27], v[26:27], v[64:65] op_sel_hi:[1,0]
	v_pk_mul_f32 v[24:25], v[24:25], v[64:65] op_sel_hi:[1,0]
	v_pk_mul_f32 v[22:23], v[22:23], v[64:65] op_sel_hi:[1,0]
	v_pk_mul_f32 v[20:21], v[20:21], v[64:65] op_sel_hi:[1,0]
	v_pk_mul_f32 v[18:19], v[18:19], v[64:65] op_sel_hi:[1,0]
	v_pk_mul_f32 v[16:17], v[16:17], v[64:65] op_sel_hi:[1,0]
	v_pk_mul_f32 v[62:63], v[62:63], v[64:65] op_sel_hi:[1,0]
	v_pk_mul_f32 v[60:61], v[60:61], v[64:65] op_sel_hi:[1,0]
	v_pk_mul_f32 v[58:59], v[58:59], v[64:65] op_sel_hi:[1,0]
	v_pk_mul_f32 v[56:57], v[56:57], v[64:65] op_sel_hi:[1,0]
	v_pk_mul_f32 v[54:55], v[54:55], v[64:65] op_sel_hi:[1,0]
	v_pk_mul_f32 v[52:53], v[52:53], v[64:65] op_sel_hi:[1,0]
	v_pk_mul_f32 v[50:51], v[50:51], v[64:65] op_sel_hi:[1,0]
	v_pk_mul_f32 v[48:49], v[48:49], v[64:65] op_sel_hi:[1,0]
	v_pk_mul_f32 v[46:47], v[46:47], v[64:65] op_sel_hi:[1,0]
	v_pk_mul_f32 v[44:45], v[44:45], v[64:65] op_sel_hi:[1,0]
	v_pk_mul_f32 v[42:43], v[42:43], v[64:65] op_sel_hi:[1,0]
	v_pk_mul_f32 v[40:41], v[40:41], v[64:65] op_sel_hi:[1,0]
	v_pk_mul_f32 v[38:39], v[38:39], v[64:65] op_sel_hi:[1,0]
	v_pk_mul_f32 v[36:37], v[36:37], v[64:65] op_sel_hi:[1,0]
	v_pk_mul_f32 v[34:35], v[34:35], v[64:65] op_sel_hi:[1,0]
	v_pk_mul_f32 v[32:33], v[32:33], v[64:65] op_sel_hi:[1,0]
	v_pk_mul_f32 v[14:15], v[14:15], v[64:65] op_sel_hi:[1,0]
	v_pk_mul_f32 v[12:13], v[12:13], v[64:65] op_sel_hi:[1,0]
	v_pk_mul_f32 v[10:11], v[10:11], v[64:65] op_sel_hi:[1,0]
	v_pk_mul_f32 v[8:9], v[8:9], v[64:65] op_sel_hi:[1,0]
	v_pk_mul_f32 v[6:7], v[6:7], v[64:65] op_sel_hi:[1,0]
	v_pk_mul_f32 v[4:5], v[4:5], v[64:65] op_sel_hi:[1,0]
	v_pk_mul_f32 v[2:3], v[2:3], v[64:65] op_sel_hi:[1,0]
	v_pk_mul_f32 v[0:1], v[0:1], v[64:65] op_sel_hi:[1,0]
	v_mul_f32_e32 v158, v158, v64
.LBB0_260:
	v_add_co_u32_e32 v64, vcc, 0x2000, v186
	s_waitcnt lgkmcnt(0)
	s_nop 0
	v_addc_co_u32_e32 v65, vcc, 0, v187, vcc
	s_barrier
	global_load_dwordx4 v[222:225], v[64:65], off
	v_add_co_u32_e32 v64, vcc, 0x2000, v188
	v_mov_b32_e32 v191, v190
	s_nop 0
	v_addc_co_u32_e32 v65, vcc, 0, v189, vcc
	global_load_dwordx4 v[154:157], v[64:65], off
	global_load_dwordx4 v[150:153], v[182:183], off offset:384
	global_load_dwordx4 v[146:149], v[184:185], off offset:384
	ds_read_b128 v[64:67], v219
	ds_read_b128 v[192:195], v219 offset:32
	ds_read_b128 v[68:71], v219 offset:4608
	ds_read_b128 v[196:199], v219 offset:4640
	ds_read_b128 v[226:229], v219 offset:64
	ds_read_b128 v[230:233], v219 offset:96
	ds_read_b128 v[234:237], v219 offset:4672
	ds_read_b128 v[238:241], v219 offset:4704
	s_waitcnt lgkmcnt(7)
	v_mfma_f32_32x32x16_bf16 v[80:95], v[64:67], v[142:145], 0
	v_fma_f32 v72, v112, s78, -v190
	v_fma_f32 v73, v113, s78, -v191
	v_fma_f32 v74, v114, s78, -v190
	v_fma_f32 v75, v115, s78, -v191
	v_exp_f32_e32 v72, v72
	v_exp_f32_e32 v73, v73
	v_exp_f32_e32 v74, v74
	v_exp_f32_e32 v75, v75
	v_pk_add_f32 v[64:65], v[72:73], 0 op_sel_hi:[1,0]
	v_cvt_pk_bf16_f32 v112, v72, v73
	v_pk_add_f32 v[114:115], v[74:75], v[64:65]
	v_cvt_pk_bf16_f32 v113, v74, v75
	s_waitcnt lgkmcnt(5)
	v_mfma_f32_32x32x16_bf16 v[64:79], v[68:71], v[142:145], 0
	v_mfma_f32_32x32x16_bf16 v[80:95], v[192:195], v[136:139], v[80:95]
	v_fma_f32 v116, v116, s78, -v190
	v_fma_f32 v117, v117, s78, -v191
	v_fma_f32 v118, v118, s78, -v190
	v_fma_f32 v119, v119, s78, -v191
	v_exp_f32_e32 v116, v116
	v_exp_f32_e32 v117, v117
	v_exp_f32_e32 v118, v118
	v_exp_f32_e32 v119, v119
	v_pk_add_f32 v[114:115], v[116:117], v[114:115]
	s_nop 0
	v_pk_add_f32 v[160:161], v[118:119], v[114:115]
	v_cvt_pk_bf16_f32 v114, v116, v117
	v_cvt_pk_bf16_f32 v115, v118, v119
	s_waitcnt lgkmcnt(4)
	v_mfma_f32_32x32x16_bf16 v[64:79], v[196:199], v[136:139], v[64:79]
	s_waitcnt lgkmcnt(3)
	v_mfma_f32_32x32x16_bf16 v[80:95], v[226:229], v[132:135], v[80:95]
	v_fma_f32 v116, v120, s78, -v190
	v_fma_f32 v117, v121, s78, -v191
	v_fma_f32 v118, v122, s78, -v190
	v_fma_f32 v119, v123, s78, -v191
	v_exp_f32_e32 v116, v116
	v_exp_f32_e32 v117, v117
	v_exp_f32_e32 v118, v118
	v_exp_f32_e32 v119, v119
	v_pk_add_f32 v[120:121], v[116:117], v[160:161]
	v_cvt_pk_bf16_f32 v116, v116, v117
	v_pk_add_f32 v[120:121], v[118:119], v[120:121]
	v_cvt_pk_bf16_f32 v117, v118, v119
	s_waitcnt lgkmcnt(1)
	v_mfma_f32_32x32x16_bf16 v[64:79], v[234:237], v[132:135], v[64:79]
	v_mfma_f32_32x32x16_bf16 v[80:95], v[230:233], v[128:131], v[80:95]
	v_fma_f32 v118, v124, s78, -v190
	v_fma_f32 v119, v125, s78, -v191
	v_fma_f32 v122, v126, s78, -v190
	v_fma_f32 v123, v127, s78, -v191
	v_exp_f32_e32 v118, v118
	v_exp_f32_e32 v119, v119
	v_exp_f32_e32 v122, v122
	v_exp_f32_e32 v123, v123
	v_pk_add_f32 v[120:121], v[118:119], v[120:121]
	v_cvt_pk_bf16_f32 v118, v118, v119
	v_pk_add_f32 v[160:161], v[122:123], v[120:121]
	v_cvt_pk_bf16_f32 v119, v122, v123
	s_waitcnt lgkmcnt(0)
	v_mfma_f32_32x32x16_bf16 v[64:79], v[238:241], v[128:131], v[64:79]
	s_mulk_i32 s24, 0x4800
	v_add_u32_e32 v159, s24, v218
	ds_read_b128 v[120:123], v159 offset:36864
	ds_read_b128 v[124:127], v159 offset:41472
	ds_read_b128 v[192:195], v159 offset:46080
	ds_read_b128 v[196:199], v159 offset:50688
	s_addk_i32 s25, 0x4800
	s_cmp_lg_u32 s30, 2
	s_cselect_b32 s24, s25, 0
	s_add_i32 s24, s24, 0
	v_add_u32_e32 v221, s24, v180
	v_add_u32_e32 v242, s24, v178
	ds_read_b128 v[226:229], v159 offset:36896
	ds_read_b128 v[230:233], v159 offset:41504
	ds_read_b128 v[234:237], v159 offset:46112
	ds_read_b128 v[238:241], v159 offset:50720
	s_waitcnt lgkmcnt(7)
	v_mfma_f32_32x32x16_bf16 v[16:31], v[120:123], v[112:115], v[16:31]
	v_fma_f32 v96, v96, s78, -v190
	v_fma_f32 v97, v97, s78, -v191
	v_fma_f32 v98, v98, s78, -v190
	v_fma_f32 v99, v99, s78, -v191
	v_exp_f32_e32 v96, v96
	v_exp_f32_e32 v97, v97
	v_exp_f32_e32 v98, v98
	v_exp_f32_e32 v99, v99
	v_pk_add_f32 v[120:121], v[96:97], v[160:161]
	v_cvt_pk_bf16_f32 v96, v96, v97
	v_pk_add_f32 v[120:121], v[98:99], v[120:121]
	v_cvt_pk_bf16_f32 v97, v98, v99
	s_waitcnt lgkmcnt(6)
	v_mfma_f32_32x32x16_bf16 v[48:63], v[124:127], v[112:115], v[48:63]
	s_waitcnt lgkmcnt(5)
	v_mfma_f32_32x32x16_bf16 v[32:47], v[192:195], v[112:115], v[32:47]
	v_fma_f32 v98, v100, s78, -v190
	v_fma_f32 v99, v101, s78, -v191
	v_fma_f32 v100, v102, s78, -v190
	v_fma_f32 v101, v103, s78, -v191
	v_exp_f32_e32 v98, v98
	v_exp_f32_e32 v99, v99
	v_exp_f32_e32 v100, v100
	v_exp_f32_e32 v101, v101
	v_pk_add_f32 v[102:103], v[98:99], v[120:121]
	v_cvt_pk_bf16_f32 v98, v98, v99
	v_pk_add_f32 v[160:161], v[100:101], v[102:103]
	v_cvt_pk_bf16_f32 v99, v100, v101
	s_waitcnt lgkmcnt(4)
	v_mfma_f32_32x32x16_bf16 v[0:15], v[196:199], v[112:115], v[0:15]
	s_waitcnt vmcnt(3)
	ds_write_b128 v217, v[222:225] offset:18432
	ds_read_b128 v[100:103], v159 offset:36928
	ds_read_b128 v[112:115], v159 offset:41536
	ds_read_b128 v[120:123], v159 offset:46144
	ds_read_b128 v[124:127], v159 offset:50752
	s_waitcnt lgkmcnt(8)
	v_mfma_f32_32x32x16_bf16 v[16:31], v[226:229], v[116:119], v[16:31]
	v_fma_f32 v104, v104, s78, -v190
	v_fma_f32 v105, v105, s78, -v191
	v_fma_f32 v106, v106, s78, -v190
	v_fma_f32 v107, v107, s78, -v191
	v_exp_f32_e32 v104, v104
	v_exp_f32_e32 v105, v105
	v_exp_f32_e32 v106, v106
	v_exp_f32_e32 v107, v107
	v_pk_add_f32 v[160:161], v[104:105], v[160:161]
	v_cvt_pk_bf16_f32 v104, v104, v105
	v_pk_add_f32 v[160:161], v[106:107], v[160:161]
	v_cvt_pk_bf16_f32 v105, v106, v107
	s_waitcnt lgkmcnt(7)
	v_mfma_f32_32x32x16_bf16 v[48:63], v[230:233], v[116:119], v[48:63]
	s_waitcnt lgkmcnt(6)
	v_mfma_f32_32x32x16_bf16 v[32:47], v[234:237], v[116:119], v[32:47]
	v_fma_f32 v106, v108, s78, -v190
	v_fma_f32 v107, v109, s78, -v191
	v_fma_f32 v108, v110, s78, -v190
	v_fma_f32 v109, v111, s78, -v191
	v_exp_f32_e32 v106, v106
	v_exp_f32_e32 v107, v107
	v_exp_f32_e32 v108, v108
	v_exp_f32_e32 v109, v109
	v_pk_add_f32 v[110:111], v[106:107], v[160:161]
	v_cvt_pk_bf16_f32 v106, v106, v107
	v_pk_add_f32 v[160:161], v[108:109], v[110:111]
	v_cvt_pk_bf16_f32 v107, v108, v109
	s_waitcnt lgkmcnt(5)
	v_mfma_f32_32x32x16_bf16 v[0:15], v[238:241], v[116:119], v[0:15]
	s_waitcnt vmcnt(2)
	ds_write_b128 v216, v[154:157] offset:18432
	ds_read_b128 v[108:111], v159 offset:36960
	ds_read_b128 v[116:119], v159 offset:41568
	ds_read_b128 v[154:157], v159 offset:46176
	ds_read_b128 v[190:193], v159 offset:50784
	s_waitcnt lgkmcnt(8)
	v_mfma_f32_32x32x16_bf16 v[16:31], v[100:103], v[96:99], v[16:31]
	s_mov_b32 s24, 0xf149f2ca
	v_max3_f32 v100, v80, s24, v81
	v_max3_f32 v100, v100, v82, v83
	v_max3_f32 v100, v100, v84, v85
	v_max3_f32 v100, v100, v86, v87
	s_waitcnt lgkmcnt(7)
	v_mfma_f32_32x32x16_bf16 v[48:63], v[112:115], v[96:99], v[48:63]
	s_waitcnt lgkmcnt(6)
	v_mfma_f32_32x32x16_bf16 v[32:47], v[120:123], v[96:99], v[32:47]
	v_max3_f32 v100, v100, v88, v89
	v_max3_f32 v100, v100, v90, v91
	v_max3_f32 v100, v100, v92, v93
	v_max3_f32 v100, v100, v94, v95
	s_waitcnt lgkmcnt(5)
	v_mfma_f32_32x32x16_bf16 v[0:15], v[124:127], v[96:99], v[0:15]
	s_waitcnt vmcnt(1)
	ds_write_b128 v242, v[150:153] offset:36864
	s_waitcnt lgkmcnt(4)
	v_mfma_f32_32x32x16_bf16 v[16:31], v[108:111], v[104:107], v[16:31]
	v_max3_f32 v96, v100, v64, v65
	v_max3_f32 v96, v96, v66, v67
	v_max3_f32 v96, v96, v68, v69
	v_max3_f32 v96, v96, v70, v71
	s_waitcnt lgkmcnt(3)
	v_mfma_f32_32x32x16_bf16 v[48:63], v[116:119], v[104:107], v[48:63]
	s_waitcnt lgkmcnt(2)
	v_mfma_f32_32x32x16_bf16 v[32:47], v[154:157], v[104:107], v[32:47]
	v_max3_f32 v96, v96, v72, v73
	v_max3_f32 v96, v96, v74, v75
	v_max3_f32 v96, v96, v76, v77
	v_max3_f32 v96, v96, v78, v79
	s_waitcnt lgkmcnt(1)
	v_mfma_f32_32x32x16_bf16 v[0:15], v[190:193], v[104:107], v[0:15]
	s_waitcnt vmcnt(0)
	ds_write_b128 v221, v[146:149] offset:36864
	v_add_f32_e32 v97, v160, v161
	v_add_f32_e32 v191, v158, v97
	v_mov_b32_e32 v97, v96
	s_nop 1
	v_permlane32_swap_b32_e32 v96, v97
	v_max_f32_e32 v96, v96, v97
	v_sub_f32_e32 v97, v96, v220
	v_mul_f32_e32 v97, 0x3e38aa3b, v97
	v_cmp_lt_f32_e32 vcc, s5, v97
	s_movk_i32 s27, 0x2000
	s_cbranch_vccz .LBB0_257
	v_max_f32_e32 v96, v96, v96
	v_max_f32_e32 v97, v220, v220
	v_max_f32_e32 v97, v97, v96
	v_sub_f32_e32 v96, v220, v97
	v_mul_f32_e32 v96, 0x3e38aa3b, v96
	v_exp_f32_e32 v96, v96
	v_mov_b32_e32 v220, v97
	v_pk_mul_f32 v[30:31], v[30:31], v[96:97] op_sel_hi:[1,0]
	v_pk_mul_f32 v[28:29], v[28:29], v[96:97] op_sel_hi:[1,0]
	v_pk_mul_f32 v[26:27], v[26:27], v[96:97] op_sel_hi:[1,0]
	v_pk_mul_f32 v[24:25], v[24:25], v[96:97] op_sel_hi:[1,0]
	v_pk_mul_f32 v[22:23], v[22:23], v[96:97] op_sel_hi:[1,0]
	v_pk_mul_f32 v[20:21], v[20:21], v[96:97] op_sel_hi:[1,0]
	v_pk_mul_f32 v[18:19], v[18:19], v[96:97] op_sel_hi:[1,0]
	v_pk_mul_f32 v[16:17], v[16:17], v[96:97] op_sel_hi:[1,0]
	v_pk_mul_f32 v[62:63], v[62:63], v[96:97] op_sel_hi:[1,0]
	v_pk_mul_f32 v[60:61], v[60:61], v[96:97] op_sel_hi:[1,0]
	v_pk_mul_f32 v[58:59], v[58:59], v[96:97] op_sel_hi:[1,0]
	v_pk_mul_f32 v[56:57], v[56:57], v[96:97] op_sel_hi:[1,0]
	v_pk_mul_f32 v[54:55], v[54:55], v[96:97] op_sel_hi:[1,0]
	v_pk_mul_f32 v[52:53], v[52:53], v[96:97] op_sel_hi:[1,0]
	v_pk_mul_f32 v[50:51], v[50:51], v[96:97] op_sel_hi:[1,0]
	v_pk_mul_f32 v[48:49], v[48:49], v[96:97] op_sel_hi:[1,0]
	v_pk_mul_f32 v[46:47], v[46:47], v[96:97] op_sel_hi:[1,0]
	v_pk_mul_f32 v[44:45], v[44:45], v[96:97] op_sel_hi:[1,0]
	v_pk_mul_f32 v[42:43], v[42:43], v[96:97] op_sel_hi:[1,0]
	v_pk_mul_f32 v[40:41], v[40:41], v[96:97] op_sel_hi:[1,0]
	v_pk_mul_f32 v[38:39], v[38:39], v[96:97] op_sel_hi:[1,0]
	v_pk_mul_f32 v[36:37], v[36:37], v[96:97] op_sel_hi:[1,0]
	v_pk_mul_f32 v[34:35], v[34:35], v[96:97] op_sel_hi:[1,0]
	v_pk_mul_f32 v[32:33], v[32:33], v[96:97] op_sel_hi:[1,0]
	v_pk_mul_f32 v[14:15], v[14:15], v[96:97] op_sel_hi:[1,0]
	v_pk_mul_f32 v[12:13], v[12:13], v[96:97] op_sel_hi:[1,0]
	v_pk_mul_f32 v[10:11], v[10:11], v[96:97] op_sel_hi:[1,0]
	v_pk_mul_f32 v[8:9], v[8:9], v[96:97] op_sel_hi:[1,0]
	v_pk_mul_f32 v[6:7], v[6:7], v[96:97] op_sel_hi:[1,0]
	v_pk_mul_f32 v[4:5], v[4:5], v[96:97] op_sel_hi:[1,0]
	v_pk_mul_f32 v[2:3], v[2:3], v[96:97] op_sel_hi:[1,0]
	v_pk_mul_f32 v[0:1], v[0:1], v[96:97] op_sel_hi:[1,0]
	v_mul_f32_e32 v191, v191, v96
	s_branch .LBB0_257
